# P3 K-loop gets the same MFMA issue order (accumulator chain + shared source on every consecutive pair)
# speedup vs baseline: 1.0253x; 1.0011x over previous
; #define PG8_LAS __attribute__((address_space(3)))
; #define PG8_STAGE(bufoff, gbase, voff) do { _Pragma("unroll") for (int _i = 0; _i < 2; ++_i) \
;         __builtin_amdgcn_global_load_lds((const unsigned*)((const char*)(gbase) + (voff)[_i]), (PG8_LAS unsigned*)(lds + (bufoff) + ldsw + _i * 8192), 16, 0, 0); } while (0)
; #define PG8_LDA(dst, b, h) do { _Pragma("unroll") for (int m = 0; m < 4; ++m) _Pragma("unroll") for (int k = 0; k < 2; ++k) dst[m][k] = *(const PG8_LAS bf16x8*)(lds + PG8_SA(b, h) + aoff + m * 2048 + k * 1024); } while (0)
; #define PG8_LDB(dst, b, h) do { _Pragma("unroll") for (int n = 0; n < 2; ++n) _Pragma("unroll") for (int k = 0; k < 2; ++k) dst[n][k] = *(const PG8_LAS bf16x8*)(lds + PG8_SB(b, h) + boff + n * 2048 + k * 1024); } while (0)
; template <class Epi, class Sched, bool ALIGN_EPI = false, bool SP2 = false, bool RS = false, bool BPRE = false>
; __device__ __forceinline__ void gemm_phase(PG8_LAS unsigned char* lds, const Gemm g, const Sched& S, const Epi& E, const float* rs_ss = nullptr, PG8_LAS float* rs_tab = nullptr) {
;     ...
;         for (int t = 0; t < nt; t += 2) {
;             const bool last = (t == nt - 2);
;             if constexpr (RS) { if (t == 16 || t == 32) { const PG8_LAS float* tp = rs_tab + (ui & 1) * 768 + (t == 32 ? 256 : 0);
;                 _Pragma("unroll") for (int a = 0; a < 2; ++a) _Pragma("unroll") for (int m = 0; m < 4; ++m) { const float f = tp[a * HALF + wr * 64 + m * 16 + fr];
;                     _Pragma("unroll") for (int b = 0; b < 2; ++b) _Pragma("unroll") for (int n = 0; n < 2; ++n) acc[a][b][m][n] = acc[a][b][m][n] * f; } } }
;             const char* a1 = cA + (size_t)(t + 1) * kstep;
;             const char* a2 = last ? nA : cA + (size_t)(t + 2) * kstep; const char* b2 = last ? nB : cB + (size_t)(t + 2) * kstep;
;             const char* a3 = a2 + kstep; const char* b3 = b2 + kstep;
;             if (last && has_next) S.a_ready(nxt);
;             if constexpr (SP2) {
;             PG8_LDB(B0, 0, 0); PG8_LDB(B1, 0, 1); PG8_SCHED; PG8_LDA(At, 0, 0); PG8_STAGE(PG8_SA(1, 1), a1 + hstep, voffA);
;             PG8_WAIT_V(8); PG8_WAIT_L(0); PG8_BAR; PG8_MMA(0, 0, At, B0); PG8_MMA(0, 1, At, B1); PG8_BAR; PG8_SCHED;
;             PG8_LDA(At, 0, 1); PG8_STAGE(PG8_SB(0, 0), b2, voffB); PG8_STAGE(PG8_SB(0, 1), b2 + hstep, voffB); PG8_STAGE(PG8_SA(0, 0), a2, voffA);
.LBB0_751:
	s_bitcmp1_b32 s40, 0
	v_mov_b32_e32 v4, v2
	v_mov_b32_e32 v5, v2
	s_cselect_b32 s6, 0xc00, 0
	s_add_u32 s71, s38, 0x8000
	v_mov_b32_e32 v3, v2
	s_waitcnt lgkmcnt(0)
	s_waitcnt vmcnt(0)
	s_mov_b32 s73, 0
	v_add_u32_e32 v158, s6, v151
	v_lshl_add_u64 v[146:147], s[10:11], 0, v[138:139]
	v_lshl_add_u64 v[148:149], s[10:11], 0, v[140:141]
	s_addc_u32 s72, s39, 0
	s_mov_b64 s[6:7], 0
	s_add_u32 s38, s10, s6
	v_add_u32_e32 v3, s64, v150
	s_addc_u32 s39, s11, s7
	ds_read_b128 v[160:163], v3
	ds_read_b128 v[164:167], v3 offset:1024
	ds_read_b128 v[168:171], v3 offset:2048
	ds_read_b128 v[172:175], v3 offset:3072
	v_add_u32_e32 v3, s65, v150
	s_add_u32 s38, s38, 0x8000
	ds_read_b128 v[176:179], v3
	ds_read_b128 v[180:183], v3 offset:1024
	ds_read_b128 v[184:187], v3 offset:2048
	ds_read_b128 v[188:191], v3 offset:3072
	s_addc_u32 s39, s39, 0
	s_add_u32 s40, s71, s6
	s_addc_u32 s41, s72, s7
	s_cmp_eq_u32 s6, 0xb8000
	s_cselect_b32 s42, s20, s38
	s_cselect_b32 s43, s21, s39
	s_cselect_b32 s40, s36, s40
	s_cselect_b32 s41, s37, s41
	s_add_u32 s38, s42, 0x4000
	s_addc_u32 s39, s43, 0
	v_lshl_add_u64 v[4:5], v[146:147], 0, s[6:7]
	s_add_i32 m0, s55, 0xc000
	ds_read_b128 v[192:195], v154
	ds_read_b128 v[196:199], v154 offset:1024
	ds_read_b128 v[200:203], v154 offset:2048
	ds_read_b128 v[204:207], v154 offset:3072
	ds_read_b128 v[208:211], v154 offset:4096
	ds_read_b128 v[212:215], v154 offset:5120
	ds_read_b128 v[216:219], v154 offset:6144
	ds_read_b128 v[220:223], v154 offset:7168
	global_load_lds_dwordx4 v[4:5], off
	v_lshl_add_u64 v[4:5], v[148:149], 0, s[6:7]
	s_add_i32 m0, s55, 0xe000
	s_nop 0
	global_load_lds_dwordx4 v[4:5], off
	s_waitcnt vmcnt(8)
	s_waitcnt lgkmcnt(0)
	s_barrier
	s_setprio 1
	s_waitcnt lgkmcnt(0)
	v_mfma_f32_16x16x32_bf16 v[130:133], v[160:163], v[192:195], 0
	v_mfma_f32_16x16x32_bf16 v[130:133], v[164:167], v[196:199], v[130:133]
	v_mfma_f32_16x16x32_bf16 v[126:129], v[172:175], v[196:199], 0
	v_mfma_f32_16x16x32_bf16 v[126:129], v[168:171], v[192:195], v[126:129]
	v_mfma_f32_16x16x32_bf16 v[110:113], v[168:171], v[200:203], 0
	v_mfma_f32_16x16x32_bf16 v[110:113], v[172:175], v[204:207], v[110:113]
	v_mfma_f32_16x16x32_bf16 v[114:117], v[164:167], v[204:207], 0
	v_mfma_f32_16x16x32_bf16 v[114:117], v[160:163], v[200:203], v[114:117]
	v_mfma_f32_16x16x32_bf16 v[98:101], v[160:163], v[208:211], 0
	v_mfma_f32_16x16x32_bf16 v[98:101], v[164:167], v[212:215], v[98:101]
	v_mfma_f32_16x16x32_bf16 v[94:97], v[172:175], v[212:215], 0
	v_mfma_f32_16x16x32_bf16 v[94:97], v[168:171], v[208:211], v[94:97]
	v_mfma_f32_16x16x32_bf16 v[78:81], v[168:171], v[216:219], 0
	v_mfma_f32_16x16x32_bf16 v[78:81], v[172:175], v[220:223], v[78:81]
	v_mfma_f32_16x16x32_bf16 v[82:85], v[164:167], v[220:223], 0
	v_mfma_f32_16x16x32_bf16 v[82:85], v[160:163], v[216:219], v[82:85]
	s_setprio 0
	s_setprio 1
	v_mfma_f32_16x16x32_bf16 v[122:125], v[176:179], v[192:195], 0
	v_mfma_f32_16x16x32_bf16 v[122:125], v[180:183], v[196:199], v[122:125]
	v_mfma_f32_16x16x32_bf16 v[118:121], v[188:191], v[196:199], 0
	v_mfma_f32_16x16x32_bf16 v[118:121], v[184:187], v[192:195], v[118:121]
	v_mfma_f32_16x16x32_bf16 v[102:105], v[184:187], v[200:203], 0
	v_mfma_f32_16x16x32_bf16 v[102:105], v[188:191], v[204:207], v[102:105]
	v_mfma_f32_16x16x32_bf16 v[106:109], v[180:183], v[204:207], 0
	v_mfma_f32_16x16x32_bf16 v[106:109], v[176:179], v[200:203], v[106:109]
	v_mfma_f32_16x16x32_bf16 v[90:93], v[176:179], v[208:211], 0
	v_mfma_f32_16x16x32_bf16 v[90:93], v[180:183], v[212:215], v[90:93]
	v_mfma_f32_16x16x32_bf16 v[86:89], v[188:191], v[212:215], 0
	v_mfma_f32_16x16x32_bf16 v[86:89], v[184:187], v[208:211], v[86:89]
	v_mfma_f32_16x16x32_bf16 v[70:73], v[184:187], v[216:219], 0
	v_mfma_f32_16x16x32_bf16 v[70:73], v[188:191], v[220:223], v[70:73]
	v_mfma_f32_16x16x32_bf16 v[74:77], v[180:183], v[220:223], 0
	v_mfma_f32_16x16x32_bf16 v[74:77], v[176:179], v[216:219], v[74:77]
	s_setprio 0
	s_barrier
	s_add_i32 s74, s64, s54
	v_lshl_add_u64 v[4:5], s[40:41], 0, v[134:135]
	s_mov_b32 m0, s74
	ds_read_b128 v[192:195], v154 offset:16384
	ds_read_b128 v[196:199], v154 offset:17408
	ds_read_b128 v[200:203], v154 offset:18432
	ds_read_b128 v[204:207], v154 offset:19456
	ds_read_b128 v[208:211], v154 offset:20480
	ds_read_b128 v[212:215], v154 offset:21504
	ds_read_b128 v[216:219], v154 offset:22528
	ds_read_b128 v[220:223], v154 offset:23552
	global_load_lds_dwordx4 v[4:5], off
	s_add_i32 m0, s74, 0x2000
	s_add_u32 s74, s40, 0xc0000
	v_lshl_add_u64 v[4:5], s[40:41], 0, v[136:137]
	s_addc_u32 s75, s41, 0
	s_add_i32 s76, s65, s54
	global_load_lds_dwordx4 v[4:5], off
	v_lshl_add_u64 v[4:5], s[74:75], 0, v[134:135]
	s_mov_b32 m0, s76
	s_nop 0
	global_load_lds_dwordx4 v[4:5], off
	v_lshl_add_u64 v[4:5], s[74:75], 0, v[136:137]
	s_add_i32 m0, s76, 0x2000
	s_nop 0
	global_load_lds_dwordx4 v[4:5], off
	v_lshl_add_u64 v[4:5], s[42:43], 0, v[134:135]
	s_mov_b32 m0, s55
	s_nop 0
	global_load_lds_dwordx4 v[4:5], off
	v_lshl_add_u64 v[4:5], s[42:43], 0, v[136:137]
	s_mov_b32 m0, s56
	s_nop 0
	global_load_lds_dwordx4 v[4:5], off
	s_waitcnt vmcnt(8)
	s_waitcnt lgkmcnt(0)
	s_barrier
; #define PG8_STAGE(bufoff, gbase, voff) do { _Pragma("unroll") for (int _i = 0; _i < 2; ++_i) \
;         __builtin_amdgcn_global_load_lds((const unsigned*)((const char*)(gbase) + (voff)[_i]), (PG8_LAS unsigned*)(lds + (bufoff) + ldsw + _i * 8192), 16, 0, 0); } while (0)
; #define PG8_LDA(dst, b, h) do { _Pragma("unroll") for (int m = 0; m < 4; ++m) _Pragma("unroll") for (int k = 0; k < 2; ++k) dst[m][k] = *(const PG8_LAS bf16x8*)(lds + PG8_SA(b, h) + aoff + m * 2048 + k * 1024); } while (0)
; #define PG8_LDB(dst, b, h) do { _Pragma("unroll") for (int n = 0; n < 2; ++n) _Pragma("unroll") for (int k = 0; k < 2; ++k) dst[n][k] = *(const PG8_LAS bf16x8*)(lds + PG8_SB(b, h) + boff + n * 2048 + k * 1024); } while (0)
; #define PG8_MMA(ai, bj, At, Bt) do { __builtin_amdgcn_s_setprio(1); _Pragma("unroll") for (int m = 0; m < 4; ++m) _Pragma("unroll") for (int n = 0; n < 2; ++n) _Pragma("unroll") for (int k = 0; k < 2; ++k) \
;         acc[ai][bj][m][n] = __builtin_amdgcn_mfma_f32_16x16x32_bf16(Bt[n][k], At[m][k], acc[ai][bj][m][n], 0, 0, 0); __builtin_amdgcn_s_setprio(0); } while (0)
; #define PG8_WAIT_V(n) asm volatile("s_waitcnt vmcnt(" #n ")" ::: "memory")
; #define PG8_WAIT_L(n) asm volatile("s_waitcnt lgkmcnt(" #n ")" ::: "memory")
; #define PG8_BAR __builtin_amdgcn_s_barrier()
; #define PG8_SCHED __builtin_amdgcn_sched_barrier(0)
; template <class Epi, class Sched, bool ALIGN_EPI = false, bool SP2 = false, bool RS = false, bool BPRE = false>
; __device__ __forceinline__ void gemm_phase(PG8_LAS unsigned char* lds, const Gemm g, const Sched& S, const Epi& E, const float* rs_ss = nullptr, PG8_LAS float* rs_tab = nullptr) {
;     ...
;             PG8_LDA(At, 0, 1); PG8_STAGE(PG8_SB(0, 0), b2, voffB); PG8_STAGE(PG8_SB(0, 1), b2 + hstep, voffB); PG8_STAGE(PG8_SA(0, 0), a2, voffA);
;             PG8_WAIT_V(8); PG8_WAIT_L(0); PG8_BAR; PG8_MMA(1, 0, At, B0); PG8_MMA(1, 1, At, B1); PG8_BAR; PG8_SCHED;
;             PG8_LDB(B0, 1, 0); PG8_LDB(B1, 1, 1); PG8_SCHED; PG8_LDA(At, 1, 0); PG8_STAGE(PG8_SA(0, 1), a2 + hstep, voffA);
;             PG8_WAIT_V(8); PG8_WAIT_L(0); PG8_BAR; PG8_MMA(0, 0, At, B0); PG8_MMA(0, 1, At, B1); PG8_BAR; PG8_SCHED;
	s_setprio 1
	s_waitcnt lgkmcnt(0)
	v_mfma_f32_16x16x32_bf16 v[66:69], v[160:163], v[192:195], 0
	v_mfma_f32_16x16x32_bf16 v[66:69], v[164:167], v[196:199], v[66:69]
	v_mfma_f32_16x16x32_bf16 v[62:65], v[172:175], v[196:199], 0
	v_mfma_f32_16x16x32_bf16 v[62:65], v[168:171], v[192:195], v[62:65]
	v_mfma_f32_16x16x32_bf16 v[46:49], v[168:171], v[200:203], 0
	v_mfma_f32_16x16x32_bf16 v[46:49], v[172:175], v[204:207], v[46:49]
	v_mfma_f32_16x16x32_bf16 v[50:53], v[164:167], v[204:207], 0
	v_mfma_f32_16x16x32_bf16 v[50:53], v[160:163], v[200:203], v[50:53]
	v_mfma_f32_16x16x32_bf16 v[34:37], v[160:163], v[208:211], 0
	v_mfma_f32_16x16x32_bf16 v[34:37], v[164:167], v[212:215], v[34:37]
	v_mfma_f32_16x16x32_bf16 v[30:33], v[172:175], v[212:215], 0
	v_mfma_f32_16x16x32_bf16 v[30:33], v[168:171], v[208:211], v[30:33]
	v_mfma_f32_16x16x32_bf16 v[14:17], v[168:171], v[216:219], 0
	v_mfma_f32_16x16x32_bf16 v[14:17], v[172:175], v[220:223], v[14:17]
	v_mfma_f32_16x16x32_bf16 v[18:21], v[164:167], v[220:223], 0
	v_mfma_f32_16x16x32_bf16 v[18:21], v[160:163], v[216:219], v[18:21]
	s_setprio 0
	s_setprio 1
	v_mfma_f32_16x16x32_bf16 v[58:61], v[176:179], v[192:195], 0
	v_mfma_f32_16x16x32_bf16 v[58:61], v[180:183], v[196:199], v[58:61]
	v_mfma_f32_16x16x32_bf16 v[54:57], v[188:191], v[196:199], 0
	v_mfma_f32_16x16x32_bf16 v[54:57], v[184:187], v[192:195], v[54:57]
	v_mfma_f32_16x16x32_bf16 v[38:41], v[184:187], v[200:203], 0
	v_mfma_f32_16x16x32_bf16 v[38:41], v[188:191], v[204:207], v[38:41]
	v_mfma_f32_16x16x32_bf16 v[42:45], v[180:183], v[204:207], 0
	v_mfma_f32_16x16x32_bf16 v[42:45], v[176:179], v[200:203], v[42:45]
	v_mfma_f32_16x16x32_bf16 v[26:29], v[176:179], v[208:211], 0
	v_mfma_f32_16x16x32_bf16 v[26:29], v[180:183], v[212:215], v[26:29]
	v_mfma_f32_16x16x32_bf16 v[22:25], v[188:191], v[212:215], 0
	v_mfma_f32_16x16x32_bf16 v[22:25], v[184:187], v[208:211], v[22:25]
	v_mfma_f32_16x16x32_bf16 v[4:7], v[184:187], v[216:219], 0
	v_mfma_f32_16x16x32_bf16 v[4:7], v[188:191], v[220:223], v[4:7]
	v_mfma_f32_16x16x32_bf16 v[10:13], v[180:183], v[220:223], 0
	v_mfma_f32_16x16x32_bf16 v[10:13], v[176:179], v[216:219], v[10:13]
	s_setprio 0
	s_barrier
	s_add_i32 s74, 0, 0x18000
	v_add_u32_e32 v3, s74, v150
	s_add_i32 s75, 0, 0x1c000
	ds_read_b128 v[160:163], v3
	ds_read_b128 v[164:167], v3 offset:1024
	ds_read_b128 v[168:171], v3 offset:2048
	ds_read_b128 v[172:175], v3 offset:3072
	v_add_u32_e32 v3, s75, v150
	ds_read_b128 v[176:179], v3
	ds_read_b128 v[180:183], v3 offset:1024
	ds_read_b128 v[184:187], v3 offset:2048
	ds_read_b128 v[188:191], v3 offset:3072
	s_add_u32 s42, s42, 0xc0000
	s_addc_u32 s43, s43, 0
	s_mov_b32 m0, s57
	v_lshl_add_u64 v[8:9], s[42:43], 0, v[134:135]
	ds_read_b128 v[192:195], v154 offset:32768
	ds_read_b128 v[196:199], v154 offset:33792
	ds_read_b128 v[200:203], v154 offset:34816
	ds_read_b128 v[204:207], v154 offset:35840
	ds_read_b128 v[208:211], v154 offset:36864
	ds_read_b128 v[212:215], v154 offset:37888
	ds_read_b128 v[216:219], v154 offset:38912
	ds_read_b128 v[220:223], v154 offset:39936
	global_load_lds_dwordx4 v[8:9], off
	v_lshl_add_u64 v[8:9], s[42:43], 0, v[136:137]
	s_mov_b32 m0, s58
	s_nop 0
	global_load_lds_dwordx4 v[8:9], off
	s_waitcnt vmcnt(8)
	s_waitcnt lgkmcnt(0)
	s_barrier
	s_setprio 1
	s_waitcnt lgkmcnt(0)
	v_mfma_f32_16x16x32_bf16 v[130:133], v[160:163], v[192:195], v[130:133]
	v_mfma_f32_16x16x32_bf16 v[130:133], v[164:167], v[196:199], v[130:133]
	v_mfma_f32_16x16x32_bf16 v[126:129], v[172:175], v[196:199], v[126:129]
	v_mfma_f32_16x16x32_bf16 v[126:129], v[168:171], v[192:195], v[126:129]
	v_mfma_f32_16x16x32_bf16 v[110:113], v[168:171], v[200:203], v[110:113]
	v_mfma_f32_16x16x32_bf16 v[110:113], v[172:175], v[204:207], v[110:113]
	v_mfma_f32_16x16x32_bf16 v[114:117], v[164:167], v[204:207], v[114:117]
	v_mfma_f32_16x16x32_bf16 v[114:117], v[160:163], v[200:203], v[114:117]
	v_mfma_f32_16x16x32_bf16 v[98:101], v[160:163], v[208:211], v[98:101]
	v_mfma_f32_16x16x32_bf16 v[98:101], v[164:167], v[212:215], v[98:101]
	v_mfma_f32_16x16x32_bf16 v[94:97], v[172:175], v[212:215], v[94:97]
	v_mfma_f32_16x16x32_bf16 v[94:97], v[168:171], v[208:211], v[94:97]
	v_mfma_f32_16x16x32_bf16 v[78:81], v[168:171], v[216:219], v[78:81]
	v_mfma_f32_16x16x32_bf16 v[78:81], v[172:175], v[220:223], v[78:81]
	v_mfma_f32_16x16x32_bf16 v[82:85], v[164:167], v[220:223], v[82:85]
	v_mfma_f32_16x16x32_bf16 v[82:85], v[160:163], v[216:219], v[82:85]
	s_setprio 0
	s_setprio 1
	v_mfma_f32_16x16x32_bf16 v[122:125], v[176:179], v[192:195], v[122:125]
	v_mfma_f32_16x16x32_bf16 v[122:125], v[180:183], v[196:199], v[122:125]
	v_mfma_f32_16x16x32_bf16 v[118:121], v[188:191], v[196:199], v[118:121]
	v_mfma_f32_16x16x32_bf16 v[118:121], v[184:187], v[192:195], v[118:121]
	v_mfma_f32_16x16x32_bf16 v[102:105], v[184:187], v[200:203], v[102:105]
	v_mfma_f32_16x16x32_bf16 v[102:105], v[188:191], v[204:207], v[102:105]
	v_mfma_f32_16x16x32_bf16 v[106:109], v[180:183], v[204:207], v[106:109]
	v_mfma_f32_16x16x32_bf16 v[106:109], v[176:179], v[200:203], v[106:109]
	v_mfma_f32_16x16x32_bf16 v[90:93], v[176:179], v[208:211], v[90:93]
	v_mfma_f32_16x16x32_bf16 v[90:93], v[180:183], v[212:215], v[90:93]
	v_mfma_f32_16x16x32_bf16 v[86:89], v[188:191], v[212:215], v[86:89]
	v_mfma_f32_16x16x32_bf16 v[86:89], v[184:187], v[208:211], v[86:89]
	v_mfma_f32_16x16x32_bf16 v[70:73], v[184:187], v[216:219], v[70:73]
	v_mfma_f32_16x16x32_bf16 v[70:73], v[188:191], v[220:223], v[70:73]
	v_mfma_f32_16x16x32_bf16 v[74:77], v[180:183], v[220:223], v[74:77]
	v_mfma_f32_16x16x32_bf16 v[74:77], v[176:179], v[216:219], v[74:77]
	s_setprio 0
	s_barrier
; #define PG8_STAGE(bufoff, gbase, voff) do { _Pragma("unroll") for (int _i = 0; _i < 2; ++_i) \
;         __builtin_amdgcn_global_load_lds((const unsigned*)((const char*)(gbase) + (voff)[_i]), (PG8_LAS unsigned*)(lds + (bufoff) + ldsw + _i * 8192), 16, 0, 0); } while (0)
; #define PG8_LDA(dst, b, h) do { _Pragma("unroll") for (int m = 0; m < 4; ++m) _Pragma("unroll") for (int k = 0; k < 2; ++k) dst[m][k] = *(const PG8_LAS bf16x8*)(lds + PG8_SA(b, h) + aoff + m * 2048 + k * 1024); } while (0)
; #define PG8_LDB(dst, b, h) do { _Pragma("unroll") for (int n = 0; n < 2; ++n) _Pragma("unroll") for (int k = 0; k < 2; ++k) dst[n][k] = *(const PG8_LAS bf16x8*)(lds + PG8_SB(b, h) + boff + n * 2048 + k * 1024); } while (0)
; #define PG8_WAIT_V(n) asm volatile("s_waitcnt vmcnt(" #n ")" ::: "memory")
; #define PG8_WAIT_L(n) asm volatile("s_waitcnt lgkmcnt(" #n ")" ::: "memory")
; #define PG8_BAR __builtin_amdgcn_s_barrier()
; #define PG8_SCHED __builtin_amdgcn_sched_barrier(0)
; template <class Epi, class Sched, bool ALIGN_EPI = false, bool SP2 = false, bool RS = false, bool BPRE = false>
; __device__ __forceinline__ void gemm_phase(PG8_LAS unsigned char* lds, const Gemm g, const Sched& S, const Epi& E, const float* rs_ss = nullptr, PG8_LAS float* rs_tab = nullptr) {
;     ...
;             PG8_LDB(B0, 0, 0); PG8_LDB(B1, 0, 1); PG8_SCHED; PG8_LDA(At, 0, 0); PG8_STAGE(PG8_SA(1, 1), a1 + hstep, voffA);
;             PG8_WAIT_V(8); PG8_WAIT_L(0); PG8_BAR; PG8_MMA(0, 0, At, B0); PG8_MMA(0, 1, At, B1); PG8_BAR; PG8_SCHED;
;             PG8_LDA(At, 0, 1); PG8_STAGE(PG8_SB(0, 0), b2, voffB); PG8_STAGE(PG8_SB(0, 1), b2 + hstep, voffB); PG8_STAGE(PG8_SA(0, 0), a2, voffA);
;             PG8_WAIT_V(8); PG8_WAIT_L(0); PG8_BAR; PG8_MMA(1, 0, At, B0); PG8_MMA(1, 1, At, B1); PG8_BAR; PG8_SCHED;
;             PG8_LDB(B0, 1, 0); PG8_LDB(B1, 1, 1); PG8_SCHED; PG8_LDA(At, 1, 0); PG8_STAGE(PG8_SA(0, 1), a2 + hstep, voffA);
;             PG8_WAIT_V(8); PG8_WAIT_L(0); PG8_BAR; PG8_MMA(0, 0, At, B0); PG8_MMA(0, 1, At, B1); PG8_BAR; PG8_SCHED;
;             PG8_LDA(At, 1, 1); PG8_STAGE(PG8_SB(1, 0), b3, voffB); PG8_STAGE(PG8_SB(1, 1), b3 + hstep, voffB); PG8_STAGE(PG8_SA(1, 0), a3, voffA);
;             PG8_WAIT_V(8); PG8_WAIT_L(0); PG8_BAR; PG8_MMA(1, 0, At, B0); PG8_MMA(1, 1, At, B1); PG8_BAR; PG8_SCHED;
	s_add_u32 s42, s40, 0x4000
	s_addc_u32 s43, s41, 0
	s_add_i32 s74, s74, s54
	v_lshl_add_u64 v[8:9], s[42:43], 0, v[134:135]
	s_mov_b32 m0, s74
	ds_read_b128 v[192:195], v154 offset:49152
	ds_read_b128 v[196:199], v154 offset:50176
	ds_read_b128 v[200:203], v154 offset:51200
	ds_read_b128 v[204:207], v154 offset:52224
	ds_read_b128 v[208:211], v154 offset:53248
	ds_read_b128 v[212:215], v154 offset:54272
	ds_read_b128 v[216:219], v154 offset:55296
	ds_read_b128 v[220:223], v154 offset:56320
	global_load_lds_dwordx4 v[8:9], off
	s_add_i32 m0, s74, 0x2000
	s_add_u32 s40, s40, 0xc4000
	v_lshl_add_u64 v[8:9], s[42:43], 0, v[136:137]
	s_addc_u32 s41, s41, 0
	s_add_i32 s42, s75, s54
	global_load_lds_dwordx4 v[8:9], off
	v_lshl_add_u64 v[8:9], s[40:41], 0, v[134:135]
	s_mov_b32 m0, s42
	s_nop 0
	global_load_lds_dwordx4 v[8:9], off
	v_lshl_add_u64 v[8:9], s[40:41], 0, v[136:137]
	s_add_i32 m0, s42, 0x2000
	s_nop 0
	global_load_lds_dwordx4 v[8:9], off
	v_lshl_add_u64 v[8:9], s[38:39], 0, v[134:135]
	s_mov_b32 m0, s60
	s_nop 0
	global_load_lds_dwordx4 v[8:9], off
	v_lshl_add_u64 v[8:9], s[38:39], 0, v[136:137]
	s_mov_b32 m0, s61
	s_nop 0
	global_load_lds_dwordx4 v[8:9], off
	s_waitcnt vmcnt(8)
	s_waitcnt lgkmcnt(0)
	s_barrier
	s_setprio 1
	s_waitcnt lgkmcnt(0)
	v_mfma_f32_16x16x32_bf16 v[66:69], v[160:163], v[192:195], v[66:69]
	v_mfma_f32_16x16x32_bf16 v[66:69], v[164:167], v[196:199], v[66:69]
	v_mfma_f32_16x16x32_bf16 v[62:65], v[172:175], v[196:199], v[62:65]
	v_mfma_f32_16x16x32_bf16 v[62:65], v[168:171], v[192:195], v[62:65]
	v_mfma_f32_16x16x32_bf16 v[46:49], v[168:171], v[200:203], v[46:49]
	v_mfma_f32_16x16x32_bf16 v[46:49], v[172:175], v[204:207], v[46:49]
	v_mfma_f32_16x16x32_bf16 v[50:53], v[164:167], v[204:207], v[50:53]
	v_mfma_f32_16x16x32_bf16 v[50:53], v[160:163], v[200:203], v[50:53]
	v_mfma_f32_16x16x32_bf16 v[34:37], v[160:163], v[208:211], v[34:37]
	v_mfma_f32_16x16x32_bf16 v[34:37], v[164:167], v[212:215], v[34:37]
	v_mfma_f32_16x16x32_bf16 v[30:33], v[172:175], v[212:215], v[30:33]
	v_mfma_f32_16x16x32_bf16 v[30:33], v[168:171], v[208:211], v[30:33]
	v_mfma_f32_16x16x32_bf16 v[14:17], v[168:171], v[216:219], v[14:17]
	v_mfma_f32_16x16x32_bf16 v[14:17], v[172:175], v[220:223], v[14:17]
	v_mfma_f32_16x16x32_bf16 v[18:21], v[164:167], v[220:223], v[18:21]
	v_mfma_f32_16x16x32_bf16 v[18:21], v[160:163], v[216:219], v[18:21]
	s_setprio 0
	s_setprio 1
	v_mfma_f32_16x16x32_bf16 v[58:61], v[176:179], v[192:195], v[58:61]
	v_mfma_f32_16x16x32_bf16 v[58:61], v[180:183], v[196:199], v[58:61]
	v_mfma_f32_16x16x32_bf16 v[54:57], v[188:191], v[196:199], v[54:57]
	v_mfma_f32_16x16x32_bf16 v[54:57], v[184:187], v[192:195], v[54:57]
	v_mfma_f32_16x16x32_bf16 v[38:41], v[184:187], v[200:203], v[38:41]
	v_mfma_f32_16x16x32_bf16 v[38:41], v[188:191], v[204:207], v[38:41]
	v_mfma_f32_16x16x32_bf16 v[42:45], v[180:183], v[204:207], v[42:45]
	v_mfma_f32_16x16x32_bf16 v[42:45], v[176:179], v[200:203], v[42:45]
	v_mfma_f32_16x16x32_bf16 v[26:29], v[176:179], v[208:211], v[26:29]
	v_mfma_f32_16x16x32_bf16 v[26:29], v[180:183], v[212:215], v[26:29]
	v_mfma_f32_16x16x32_bf16 v[22:25], v[188:191], v[212:215], v[22:25]
	v_mfma_f32_16x16x32_bf16 v[22:25], v[184:187], v[208:211], v[22:25]
	v_mfma_f32_16x16x32_bf16 v[8:11], v[176:179], v[216:219], v[10:13]
	v_mfma_f32_16x16x32_bf16 v[10:13], v[180:183], v[220:223], v[8:11]
	v_mfma_f32_16x16x32_bf16 v[4:7], v[188:191], v[220:223], v[4:7]
	v_mfma_f32_16x16x32_bf16 v[6:9], v[184:187], v[216:219], v[4:7]
	s_setprio 0
	s_barrier
	s_add_i32 s38, s73, 2
	s_add_u32 s6, s6, 0x8000
	s_addc_u32 s7, s7, 0
	s_cmp_gt_u32 s73, 45
	s_mov_b32 s73, s38
	s_branch .LBB0_753
.LBB0_752:
	s_add_u32 s38, s10, s6
	v_add_u32_e32 v3, s64, v150
	s_addc_u32 s39, s11, s7
	ds_read_b128 v[160:163], v3
	ds_read_b128 v[164:167], v3 offset:1024
	ds_read_b128 v[168:171], v3 offset:2048
	ds_read_b128 v[172:175], v3 offset:3072
	v_add_u32_e32 v3, s65, v150
	s_add_u32 s38, s38, 0x8000
	ds_read_b128 v[176:179], v3
	ds_read_b128 v[180:183], v3 offset:1024
	ds_read_b128 v[184:187], v3 offset:2048
	ds_read_b128 v[188:191], v3 offset:3072
	s_addc_u32 s39, s39, 0
	s_add_u32 s40, s71, s6
	s_addc_u32 s41, s72, s7
	s_cmp_eq_u32 s6, 0xb8000
	s_cselect_b32 s42, s20, s38
	s_cselect_b32 s43, s21, s39
	s_cselect_b32 s40, s36, s40
	s_cselect_b32 s41, s37, s41
	s_add_u32 s38, s42, 0x4000
	s_addc_u32 s39, s43, 0
	v_lshl_add_u64 v[4:5], v[146:147], 0, s[6:7]
	s_add_i32 m0, s55, 0xc000
	ds_read_b128 v[192:195], v154
	ds_read_b128 v[196:199], v154 offset:1024
	ds_read_b128 v[200:203], v154 offset:2048
	ds_read_b128 v[204:207], v154 offset:3072
	ds_read_b128 v[208:211], v154 offset:4096
	ds_read_b128 v[212:215], v154 offset:5120
	ds_read_b128 v[216:219], v154 offset:6144
	ds_read_b128 v[220:223], v154 offset:7168
	global_load_lds_dwordx4 v[4:5], off
	v_lshl_add_u64 v[4:5], v[148:149], 0, s[6:7]
	s_add_i32 m0, s55, 0xe000
	s_nop 0
	global_load_lds_dwordx4 v[4:5], off
	s_waitcnt vmcnt(8)
	s_waitcnt lgkmcnt(0)
	s_barrier
; #define PG8_STAGE(bufoff, gbase, voff) do { _Pragma("unroll") for (int _i = 0; _i < 2; ++_i) \
;         __builtin_amdgcn_global_load_lds((const unsigned*)((const char*)(gbase) + (voff)[_i]), (PG8_LAS unsigned*)(lds + (bufoff) + ldsw + _i * 8192), 16, 0, 0); } while (0)
; #define PG8_LDA(dst, b, h) do { _Pragma("unroll") for (int m = 0; m < 4; ++m) _Pragma("unroll") for (int k = 0; k < 2; ++k) dst[m][k] = *(const PG8_LAS bf16x8*)(lds + PG8_SA(b, h) + aoff + m * 2048 + k * 1024); } while (0)
; #define PG8_MMA(ai, bj, At, Bt) do { __builtin_amdgcn_s_setprio(1); _Pragma("unroll") for (int m = 0; m < 4; ++m) _Pragma("unroll") for (int n = 0; n < 2; ++n) _Pragma("unroll") for (int k = 0; k < 2; ++k) \
;         acc[ai][bj][m][n] = __builtin_amdgcn_mfma_f32_16x16x32_bf16(Bt[n][k], At[m][k], acc[ai][bj][m][n], 0, 0, 0); __builtin_amdgcn_s_setprio(0); } while (0)
; #define PG8_WAIT_V(n) asm volatile("s_waitcnt vmcnt(" #n ")" ::: "memory")
; #define PG8_WAIT_L(n) asm volatile("s_waitcnt lgkmcnt(" #n ")" ::: "memory")
; #define PG8_BAR __builtin_amdgcn_s_barrier()
; #define PG8_SCHED __builtin_amdgcn_sched_barrier(0)
; template <class Epi, class Sched, bool ALIGN_EPI = false, bool SP2 = false, bool RS = false, bool BPRE = false>
; __device__ __forceinline__ void gemm_phase(PG8_LAS unsigned char* lds, const Gemm g, const Sched& S, const Epi& E, const float* rs_ss = nullptr, PG8_LAS float* rs_tab = nullptr) {
;     ...
;             PG8_WAIT_V(8); PG8_WAIT_L(0); PG8_BAR; PG8_MMA(0, 0, At, B0); PG8_MMA(0, 1, At, B1); PG8_BAR; PG8_SCHED;
;             PG8_LDA(At, 0, 1); PG8_STAGE(PG8_SB(0, 0), b2, voffB); PG8_STAGE(PG8_SB(0, 1), b2 + hstep, voffB); PG8_STAGE(PG8_SA(0, 0), a2, voffA);
;             PG8_WAIT_V(8); PG8_WAIT_L(0); PG8_BAR; PG8_MMA(1, 0, At, B0); PG8_MMA(1, 1, At, B1); PG8_BAR; PG8_SCHED;
	s_setprio 1
	s_waitcnt lgkmcnt(0)
	v_mfma_f32_16x16x32_bf16 v[130:133], v[160:163], v[192:195], v[130:133]
	v_mfma_f32_16x16x32_bf16 v[130:133], v[164:167], v[196:199], v[130:133]
	v_mfma_f32_16x16x32_bf16 v[126:129], v[172:175], v[196:199], v[126:129]
	v_mfma_f32_16x16x32_bf16 v[126:129], v[168:171], v[192:195], v[126:129]
	v_mfma_f32_16x16x32_bf16 v[110:113], v[168:171], v[200:203], v[110:113]
	v_mfma_f32_16x16x32_bf16 v[110:113], v[172:175], v[204:207], v[110:113]
	v_mfma_f32_16x16x32_bf16 v[114:117], v[164:167], v[204:207], v[114:117]
	v_mfma_f32_16x16x32_bf16 v[114:117], v[160:163], v[200:203], v[114:117]
	v_mfma_f32_16x16x32_bf16 v[98:101], v[160:163], v[208:211], v[98:101]
	v_mfma_f32_16x16x32_bf16 v[98:101], v[164:167], v[212:215], v[98:101]
	v_mfma_f32_16x16x32_bf16 v[94:97], v[172:175], v[212:215], v[94:97]
	v_mfma_f32_16x16x32_bf16 v[94:97], v[168:171], v[208:211], v[94:97]
	v_mfma_f32_16x16x32_bf16 v[78:81], v[168:171], v[216:219], v[78:81]
	v_mfma_f32_16x16x32_bf16 v[78:81], v[172:175], v[220:223], v[78:81]
	v_mfma_f32_16x16x32_bf16 v[82:85], v[164:167], v[220:223], v[82:85]
	v_mfma_f32_16x16x32_bf16 v[82:85], v[160:163], v[216:219], v[82:85]
	s_setprio 0
	s_setprio 1
	v_mfma_f32_16x16x32_bf16 v[122:125], v[176:179], v[192:195], v[122:125]
	v_mfma_f32_16x16x32_bf16 v[122:125], v[180:183], v[196:199], v[122:125]
	v_mfma_f32_16x16x32_bf16 v[118:121], v[188:191], v[196:199], v[118:121]
	v_mfma_f32_16x16x32_bf16 v[118:121], v[184:187], v[192:195], v[118:121]
	v_mfma_f32_16x16x32_bf16 v[102:105], v[184:187], v[200:203], v[102:105]
	v_mfma_f32_16x16x32_bf16 v[102:105], v[188:191], v[204:207], v[102:105]
	v_mfma_f32_16x16x32_bf16 v[106:109], v[180:183], v[204:207], v[106:109]
	v_mfma_f32_16x16x32_bf16 v[106:109], v[176:179], v[200:203], v[106:109]
	v_mfma_f32_16x16x32_bf16 v[90:93], v[176:179], v[208:211], v[90:93]
	v_mfma_f32_16x16x32_bf16 v[90:93], v[180:183], v[212:215], v[90:93]
	v_mfma_f32_16x16x32_bf16 v[86:89], v[188:191], v[212:215], v[86:89]
	v_mfma_f32_16x16x32_bf16 v[86:89], v[184:187], v[208:211], v[86:89]
	v_mfma_f32_16x16x32_bf16 v[70:73], v[184:187], v[216:219], v[70:73]
	v_mfma_f32_16x16x32_bf16 v[70:73], v[188:191], v[220:223], v[70:73]
	v_mfma_f32_16x16x32_bf16 v[74:77], v[180:183], v[220:223], v[74:77]
	v_mfma_f32_16x16x32_bf16 v[74:77], v[176:179], v[216:219], v[74:77]
	s_setprio 0
	s_barrier
	s_add_i32 s74, s64, s54
	v_lshl_add_u64 v[4:5], s[40:41], 0, v[134:135]
	s_mov_b32 m0, s74
	ds_read_b128 v[192:195], v154 offset:16384
	ds_read_b128 v[196:199], v154 offset:17408
	ds_read_b128 v[200:203], v154 offset:18432
	ds_read_b128 v[204:207], v154 offset:19456
	ds_read_b128 v[208:211], v154 offset:20480
	ds_read_b128 v[212:215], v154 offset:21504
	ds_read_b128 v[216:219], v154 offset:22528
	ds_read_b128 v[220:223], v154 offset:23552
	global_load_lds_dwordx4 v[4:5], off
	s_add_i32 m0, s74, 0x2000
	s_add_u32 s74, s40, 0xc0000
	v_lshl_add_u64 v[4:5], s[40:41], 0, v[136:137]
	s_addc_u32 s75, s41, 0
	s_add_i32 s76, s65, s54
	global_load_lds_dwordx4 v[4:5], off
	v_lshl_add_u64 v[4:5], s[74:75], 0, v[134:135]
	s_mov_b32 m0, s76
	s_nop 0
	global_load_lds_dwordx4 v[4:5], off
	v_lshl_add_u64 v[4:5], s[74:75], 0, v[136:137]
	s_add_i32 m0, s76, 0x2000
	s_nop 0
	global_load_lds_dwordx4 v[4:5], off
	v_lshl_add_u64 v[4:5], s[42:43], 0, v[134:135]
	s_mov_b32 m0, s55
	s_nop 0
	global_load_lds_dwordx4 v[4:5], off
	v_lshl_add_u64 v[4:5], s[42:43], 0, v[136:137]
	s_mov_b32 m0, s56
	s_nop 0
	global_load_lds_dwordx4 v[4:5], off
	s_waitcnt vmcnt(8)
	s_waitcnt lgkmcnt(0)
	s_barrier
	s_setprio 1
	s_waitcnt lgkmcnt(0)
	v_mfma_f32_16x16x32_bf16 v[66:69], v[160:163], v[192:195], v[66:69]
	v_mfma_f32_16x16x32_bf16 v[66:69], v[164:167], v[196:199], v[66:69]
	v_mfma_f32_16x16x32_bf16 v[62:65], v[172:175], v[196:199], v[62:65]
	v_mfma_f32_16x16x32_bf16 v[62:65], v[168:171], v[192:195], v[62:65]
	v_mfma_f32_16x16x32_bf16 v[46:49], v[168:171], v[200:203], v[46:49]
	v_mfma_f32_16x16x32_bf16 v[46:49], v[172:175], v[204:207], v[46:49]
	v_mfma_f32_16x16x32_bf16 v[50:53], v[164:167], v[204:207], v[50:53]
	v_mfma_f32_16x16x32_bf16 v[50:53], v[160:163], v[200:203], v[50:53]
	v_mfma_f32_16x16x32_bf16 v[34:37], v[160:163], v[208:211], v[34:37]
	v_mfma_f32_16x16x32_bf16 v[34:37], v[164:167], v[212:215], v[34:37]
	v_mfma_f32_16x16x32_bf16 v[30:33], v[172:175], v[212:215], v[30:33]
	v_mfma_f32_16x16x32_bf16 v[30:33], v[168:171], v[208:211], v[30:33]
	v_mfma_f32_16x16x32_bf16 v[14:17], v[168:171], v[216:219], v[14:17]
	v_mfma_f32_16x16x32_bf16 v[14:17], v[172:175], v[220:223], v[14:17]
	v_mfma_f32_16x16x32_bf16 v[18:21], v[164:167], v[220:223], v[18:21]
	v_mfma_f32_16x16x32_bf16 v[18:21], v[160:163], v[216:219], v[18:21]
	s_setprio 0
	s_setprio 1
	v_mfma_f32_16x16x32_bf16 v[58:61], v[176:179], v[192:195], v[58:61]
	v_mfma_f32_16x16x32_bf16 v[58:61], v[180:183], v[196:199], v[58:61]
	v_mfma_f32_16x16x32_bf16 v[54:57], v[188:191], v[196:199], v[54:57]
	v_mfma_f32_16x16x32_bf16 v[54:57], v[184:187], v[192:195], v[54:57]
	v_mfma_f32_16x16x32_bf16 v[38:41], v[184:187], v[200:203], v[38:41]
	v_mfma_f32_16x16x32_bf16 v[38:41], v[188:191], v[204:207], v[38:41]
	v_mfma_f32_16x16x32_bf16 v[42:45], v[180:183], v[204:207], v[42:45]
	v_mfma_f32_16x16x32_bf16 v[42:45], v[176:179], v[200:203], v[42:45]
	v_mfma_f32_16x16x32_bf16 v[26:29], v[176:179], v[208:211], v[26:29]
	v_mfma_f32_16x16x32_bf16 v[26:29], v[180:183], v[212:215], v[26:29]
	v_mfma_f32_16x16x32_bf16 v[22:25], v[188:191], v[212:215], v[22:25]
	v_mfma_f32_16x16x32_bf16 v[22:25], v[184:187], v[208:211], v[22:25]
	v_mfma_f32_16x16x32_bf16 v[4:7], v[184:187], v[216:219], v[6:9]
	v_mfma_f32_16x16x32_bf16 v[4:7], v[188:191], v[220:223], v[4:7]
	v_mfma_f32_16x16x32_bf16 v[10:13], v[180:183], v[220:223], v[10:13]
	v_mfma_f32_16x16x32_bf16 v[10:13], v[176:179], v[216:219], v[10:13]
	s_setprio 0
	s_barrier
; #define PG8_STAGE(bufoff, gbase, voff) do { _Pragma("unroll") for (int _i = 0; _i < 2; ++_i) \
;         __builtin_amdgcn_global_load_lds((const unsigned*)((const char*)(gbase) + (voff)[_i]), (PG8_LAS unsigned*)(lds + (bufoff) + ldsw + _i * 8192), 16, 0, 0); } while (0)
; #define PG8_LDA(dst, b, h) do { _Pragma("unroll") for (int m = 0; m < 4; ++m) _Pragma("unroll") for (int k = 0; k < 2; ++k) dst[m][k] = *(const PG8_LAS bf16x8*)(lds + PG8_SA(b, h) + aoff + m * 2048 + k * 1024); } while (0)
; #define PG8_LDB(dst, b, h) do { _Pragma("unroll") for (int n = 0; n < 2; ++n) _Pragma("unroll") for (int k = 0; k < 2; ++k) dst[n][k] = *(const PG8_LAS bf16x8*)(lds + PG8_SB(b, h) + boff + n * 2048 + k * 1024); } while (0)
; #define PG8_MMA(ai, bj, At, Bt) do { __builtin_amdgcn_s_setprio(1); _Pragma("unroll") for (int m = 0; m < 4; ++m) _Pragma("unroll") for (int n = 0; n < 2; ++n) _Pragma("unroll") for (int k = 0; k < 2; ++k) \
;         acc[ai][bj][m][n] = __builtin_amdgcn_mfma_f32_16x16x32_bf16(Bt[n][k], At[m][k], acc[ai][bj][m][n], 0, 0, 0); __builtin_amdgcn_s_setprio(0); } while (0)
; #define PG8_WAIT_V(n) asm volatile("s_waitcnt vmcnt(" #n ")" ::: "memory")
; #define PG8_WAIT_L(n) asm volatile("s_waitcnt lgkmcnt(" #n ")" ::: "memory")
; #define PG8_BAR __builtin_amdgcn_s_barrier()
; #define PG8_SCHED __builtin_amdgcn_sched_barrier(0)
; template <class Epi, class Sched, bool ALIGN_EPI = false, bool SP2 = false, bool RS = false, bool BPRE = false>
; __device__ __forceinline__ void gemm_phase(PG8_LAS unsigned char* lds, const Gemm g, const Sched& S, const Epi& E, const float* rs_ss = nullptr, PG8_LAS float* rs_tab = nullptr) {
;     ...
;             PG8_LDB(B0, 1, 0); PG8_LDB(B1, 1, 1); PG8_SCHED; PG8_LDA(At, 1, 0); PG8_STAGE(PG8_SA(0, 1), a2 + hstep, voffA);
;             PG8_WAIT_V(8); PG8_WAIT_L(0); PG8_BAR; PG8_MMA(0, 0, At, B0); PG8_MMA(0, 1, At, B1); PG8_BAR; PG8_SCHED;
	s_add_i32 s74, 0, 0x18000
	v_add_u32_e32 v3, s74, v150
	s_add_i32 s75, 0, 0x1c000
	ds_read_b128 v[160:163], v3
	ds_read_b128 v[164:167], v3 offset:1024
	ds_read_b128 v[168:171], v3 offset:2048
	ds_read_b128 v[172:175], v3 offset:3072
	v_add_u32_e32 v3, s75, v150
	ds_read_b128 v[176:179], v3
	ds_read_b128 v[180:183], v3 offset:1024
	ds_read_b128 v[184:187], v3 offset:2048
	ds_read_b128 v[188:191], v3 offset:3072
	s_add_u32 s42, s42, 0xc0000
	s_addc_u32 s43, s43, 0
	s_mov_b32 m0, s57
	v_lshl_add_u64 v[8:9], s[42:43], 0, v[134:135]
	ds_read_b128 v[192:195], v154 offset:32768
	ds_read_b128 v[196:199], v154 offset:33792
	ds_read_b128 v[200:203], v154 offset:34816
	ds_read_b128 v[204:207], v154 offset:35840
	ds_read_b128 v[208:211], v154 offset:36864
	ds_read_b128 v[212:215], v154 offset:37888
	ds_read_b128 v[216:219], v154 offset:38912
	ds_read_b128 v[220:223], v154 offset:39936
	global_load_lds_dwordx4 v[8:9], off
	v_lshl_add_u64 v[8:9], s[42:43], 0, v[136:137]
	s_mov_b32 m0, s58
	s_nop 0
	global_load_lds_dwordx4 v[8:9], off
	s_waitcnt vmcnt(8)
	s_waitcnt lgkmcnt(0)
	s_barrier
	s_setprio 1
	s_waitcnt lgkmcnt(0)
	v_mfma_f32_16x16x32_bf16 v[130:133], v[160:163], v[192:195], v[130:133]
	v_mfma_f32_16x16x32_bf16 v[130:133], v[164:167], v[196:199], v[130:133]
	v_mfma_f32_16x16x32_bf16 v[126:129], v[172:175], v[196:199], v[126:129]
	v_mfma_f32_16x16x32_bf16 v[126:129], v[168:171], v[192:195], v[126:129]
	v_mfma_f32_16x16x32_bf16 v[110:113], v[168:171], v[200:203], v[110:113]
	v_mfma_f32_16x16x32_bf16 v[110:113], v[172:175], v[204:207], v[110:113]
	v_mfma_f32_16x16x32_bf16 v[114:117], v[164:167], v[204:207], v[114:117]
	v_mfma_f32_16x16x32_bf16 v[114:117], v[160:163], v[200:203], v[114:117]
	v_mfma_f32_16x16x32_bf16 v[98:101], v[160:163], v[208:211], v[98:101]
	v_mfma_f32_16x16x32_bf16 v[98:101], v[164:167], v[212:215], v[98:101]
	v_mfma_f32_16x16x32_bf16 v[94:97], v[172:175], v[212:215], v[94:97]
	v_mfma_f32_16x16x32_bf16 v[94:97], v[168:171], v[208:211], v[94:97]
	v_mfma_f32_16x16x32_bf16 v[78:81], v[168:171], v[216:219], v[78:81]
	v_mfma_f32_16x16x32_bf16 v[78:81], v[172:175], v[220:223], v[78:81]
	v_mfma_f32_16x16x32_bf16 v[82:85], v[164:167], v[220:223], v[82:85]
	v_mfma_f32_16x16x32_bf16 v[82:85], v[160:163], v[216:219], v[82:85]
	s_setprio 0
	s_setprio 1
	v_mfma_f32_16x16x32_bf16 v[122:125], v[176:179], v[192:195], v[122:125]
	v_mfma_f32_16x16x32_bf16 v[122:125], v[180:183], v[196:199], v[122:125]
	v_mfma_f32_16x16x32_bf16 v[118:121], v[188:191], v[196:199], v[118:121]
	v_mfma_f32_16x16x32_bf16 v[118:121], v[184:187], v[192:195], v[118:121]
	v_mfma_f32_16x16x32_bf16 v[102:105], v[184:187], v[200:203], v[102:105]
	v_mfma_f32_16x16x32_bf16 v[102:105], v[188:191], v[204:207], v[102:105]
	v_mfma_f32_16x16x32_bf16 v[106:109], v[180:183], v[204:207], v[106:109]
	v_mfma_f32_16x16x32_bf16 v[106:109], v[176:179], v[200:203], v[106:109]
	v_mfma_f32_16x16x32_bf16 v[90:93], v[176:179], v[208:211], v[90:93]
	v_mfma_f32_16x16x32_bf16 v[90:93], v[180:183], v[212:215], v[90:93]
	v_mfma_f32_16x16x32_bf16 v[86:89], v[188:191], v[212:215], v[86:89]
	v_mfma_f32_16x16x32_bf16 v[86:89], v[184:187], v[208:211], v[86:89]
	v_mfma_f32_16x16x32_bf16 v[70:73], v[184:187], v[216:219], v[70:73]
	v_mfma_f32_16x16x32_bf16 v[70:73], v[188:191], v[220:223], v[70:73]
	v_mfma_f32_16x16x32_bf16 v[74:77], v[180:183], v[220:223], v[74:77]
	v_mfma_f32_16x16x32_bf16 v[74:77], v[176:179], v[216:219], v[74:77]
	s_setprio 0
	s_barrier
; #define PG8_STAGE(bufoff, gbase, voff) do { _Pragma("unroll") for (int _i = 0; _i < 2; ++_i) \
;         __builtin_amdgcn_global_load_lds((const unsigned*)((const char*)(gbase) + (voff)[_i]), (PG8_LAS unsigned*)(lds + (bufoff) + ldsw + _i * 8192), 16, 0, 0); } while (0)
; #define PG8_LDA(dst, b, h) do { _Pragma("unroll") for (int m = 0; m < 4; ++m) _Pragma("unroll") for (int k = 0; k < 2; ++k) dst[m][k] = *(const PG8_LAS bf16x8*)(lds + PG8_SA(b, h) + aoff + m * 2048 + k * 1024); } while (0)
; #define PG8_MMA(ai, bj, At, Bt) do { __builtin_amdgcn_s_setprio(1); _Pragma("unroll") for (int m = 0; m < 4; ++m) _Pragma("unroll") for (int n = 0; n < 2; ++n) _Pragma("unroll") for (int k = 0; k < 2; ++k) \
;         acc[ai][bj][m][n] = __builtin_amdgcn_mfma_f32_16x16x32_bf16(Bt[n][k], At[m][k], acc[ai][bj][m][n], 0, 0, 0); __builtin_amdgcn_s_setprio(0); } while (0)
; #define PG8_WAIT_V(n) asm volatile("s_waitcnt vmcnt(" #n ")" ::: "memory")
; #define PG8_WAIT_L(n) asm volatile("s_waitcnt lgkmcnt(" #n ")" ::: "memory")
; #define PG8_BAR __builtin_amdgcn_s_barrier()
; #define PG8_SCHED __builtin_amdgcn_sched_barrier(0)
; template <class Epi, class Sched, bool ALIGN_EPI = false, bool SP2 = false, bool RS = false, bool BPRE = false>
; __device__ __forceinline__ void gemm_phase(PG8_LAS unsigned char* lds, const Gemm g, const Sched& S, const Epi& E, const float* rs_ss = nullptr, PG8_LAS float* rs_tab = nullptr) {
;     ...
;             PG8_LDA(At, 1, 1); PG8_STAGE(PG8_SB(1, 0), b3, voffB); PG8_STAGE(PG8_SB(1, 1), b3 + hstep, voffB); PG8_STAGE(PG8_SA(1, 0), a3, voffA);
;             PG8_WAIT_V(8); PG8_WAIT_L(0); PG8_BAR; PG8_MMA(1, 0, At, B0); PG8_MMA(1, 1, At, B1); PG8_BAR; PG8_SCHED;
	s_add_u32 s42, s40, 0x4000
	s_addc_u32 s43, s41, 0
	s_add_i32 s74, s74, s54
	v_lshl_add_u64 v[8:9], s[42:43], 0, v[134:135]
	s_mov_b32 m0, s74
	ds_read_b128 v[192:195], v154 offset:49152
	ds_read_b128 v[196:199], v154 offset:50176
	ds_read_b128 v[200:203], v154 offset:51200
	ds_read_b128 v[204:207], v154 offset:52224
	ds_read_b128 v[208:211], v154 offset:53248
	ds_read_b128 v[212:215], v154 offset:54272
	ds_read_b128 v[216:219], v154 offset:55296
	ds_read_b128 v[220:223], v154 offset:56320
	global_load_lds_dwordx4 v[8:9], off
	s_add_i32 m0, s74, 0x2000
	s_add_u32 s40, s40, 0xc4000
	v_lshl_add_u64 v[8:9], s[42:43], 0, v[136:137]
	s_addc_u32 s41, s41, 0
	s_add_i32 s42, s75, s54
	global_load_lds_dwordx4 v[8:9], off
	v_lshl_add_u64 v[8:9], s[40:41], 0, v[134:135]
	s_mov_b32 m0, s42
	s_nop 0
	global_load_lds_dwordx4 v[8:9], off
	v_lshl_add_u64 v[8:9], s[40:41], 0, v[136:137]
	s_add_i32 m0, s42, 0x2000
	s_nop 0
	global_load_lds_dwordx4 v[8:9], off
	v_lshl_add_u64 v[8:9], s[38:39], 0, v[134:135]
	s_mov_b32 m0, s60
	s_nop 0
	global_load_lds_dwordx4 v[8:9], off
	v_lshl_add_u64 v[8:9], s[38:39], 0, v[136:137]
	s_mov_b32 m0, s61
	s_nop 0
	global_load_lds_dwordx4 v[8:9], off
	s_waitcnt vmcnt(8)
	s_waitcnt lgkmcnt(0)
	s_barrier
	s_setprio 1
	s_waitcnt lgkmcnt(0)
	v_mfma_f32_16x16x32_bf16 v[66:69], v[160:163], v[192:195], v[66:69]
	v_mfma_f32_16x16x32_bf16 v[66:69], v[164:167], v[196:199], v[66:69]
	v_mfma_f32_16x16x32_bf16 v[62:65], v[172:175], v[196:199], v[62:65]
	v_mfma_f32_16x16x32_bf16 v[62:65], v[168:171], v[192:195], v[62:65]
	v_mfma_f32_16x16x32_bf16 v[46:49], v[168:171], v[200:203], v[46:49]
	v_mfma_f32_16x16x32_bf16 v[46:49], v[172:175], v[204:207], v[46:49]
	v_mfma_f32_16x16x32_bf16 v[50:53], v[164:167], v[204:207], v[50:53]
	v_mfma_f32_16x16x32_bf16 v[50:53], v[160:163], v[200:203], v[50:53]
	v_mfma_f32_16x16x32_bf16 v[34:37], v[160:163], v[208:211], v[34:37]
	v_mfma_f32_16x16x32_bf16 v[34:37], v[164:167], v[212:215], v[34:37]
	v_mfma_f32_16x16x32_bf16 v[30:33], v[172:175], v[212:215], v[30:33]
	v_mfma_f32_16x16x32_bf16 v[30:33], v[168:171], v[208:211], v[30:33]
	v_mfma_f32_16x16x32_bf16 v[14:17], v[168:171], v[216:219], v[14:17]
	v_mfma_f32_16x16x32_bf16 v[14:17], v[172:175], v[220:223], v[14:17]
	v_mfma_f32_16x16x32_bf16 v[18:21], v[164:167], v[220:223], v[18:21]
	v_mfma_f32_16x16x32_bf16 v[18:21], v[160:163], v[216:219], v[18:21]
	s_setprio 0
	s_setprio 1
	v_mfma_f32_16x16x32_bf16 v[58:61], v[176:179], v[192:195], v[58:61]
	v_mfma_f32_16x16x32_bf16 v[58:61], v[180:183], v[196:199], v[58:61]
	v_mfma_f32_16x16x32_bf16 v[54:57], v[188:191], v[196:199], v[54:57]
	v_mfma_f32_16x16x32_bf16 v[54:57], v[184:187], v[192:195], v[54:57]
	v_mfma_f32_16x16x32_bf16 v[38:41], v[184:187], v[200:203], v[38:41]
	v_mfma_f32_16x16x32_bf16 v[38:41], v[188:191], v[204:207], v[38:41]
	v_mfma_f32_16x16x32_bf16 v[42:45], v[180:183], v[204:207], v[42:45]
	v_mfma_f32_16x16x32_bf16 v[42:45], v[176:179], v[200:203], v[42:45]
	v_mfma_f32_16x16x32_bf16 v[26:29], v[176:179], v[208:211], v[26:29]
	v_mfma_f32_16x16x32_bf16 v[26:29], v[180:183], v[212:215], v[26:29]
	v_mfma_f32_16x16x32_bf16 v[22:25], v[188:191], v[212:215], v[22:25]
	v_mfma_f32_16x16x32_bf16 v[22:25], v[184:187], v[208:211], v[22:25]
	v_mfma_f32_16x16x32_bf16 v[8:11], v[176:179], v[216:219], v[10:13]
	v_mfma_f32_16x16x32_bf16 v[10:13], v[180:183], v[220:223], v[8:11]
	v_mfma_f32_16x16x32_bf16 v[4:7], v[188:191], v[220:223], v[4:7]
	v_mfma_f32_16x16x32_bf16 v[6:9], v[184:187], v[216:219], v[4:7]
	s_setprio 0
	s_barrier
	s_add_i32 s38, s73, 2
	s_add_u32 s6, s6, 0x8000
	s_addc_u32 s7, s7, 0
	s_cmp_gt_u32 s73, 45
	s_mov_b32 s73, s38
	s_cbranch_scc1 .LBB0_759
